# early barrier in LDS-DMA GEMM loops: barrier before the last k-step MFMAs, next stage first fragment reads issued under them
# baseline (speedup 1.0000x reference)
; DI int TIDX() { int t = threadIdx.x; asm volatile("" : "+v"(t)); return t; }
; #define XCD_LOOP(Mx, ntn) const int xcd_ = BIDX() & 7; for (int u_ = BIDX() >> 3; u_ < (Mx) * (ntn); u_ += (int)(gridDim.x >> 3))
; DI void gemm_tile_deep(const h16* __restrict__ A, int lda, const h16* __restrict__ B, int ldb, int K, f32x16 (&acc)[2][2], h16* sm) {
;   const int tid = TIDX(), lane = tid & 63, w = tid >> 6, wm = w >> 1, wn = w & 1, r = lane & 31, hh = lane >> 5;
;   const unsigned ao = (unsigned)(tid >> 3) * (unsigned)lda + (unsigned)(tid & 7) * 8u;
;   const unsigned bo = (unsigned)(tid >> 3) * (unsigned)ldb + (unsigned)(tid & 7) * 8u;
;   const h16* ag = A;
;   const h16* bg = B;
;   u32x4 ra0[4], rb0[4], ra1[4], rb1[4];
; #pragma unroll
;   for (int i = 0; i < 4; ++i) {
;     ra0[i] = *(const u32x4*)(ag + (ao + (unsigned)i * 32u * (unsigned)lda));
;     rb0[i] = *(const u32x4*)(bg + (bo + (unsigned)i * 32u * (unsigned)ldb));
;   }
;   ag += 64; bg += 64;
; #pragma unroll
;   for (int i = 0; i < 4; ++i) {
;     ra1[i] = *(const u32x4*)(ag + (ao + (unsigned)i * 32u * (unsigned)lda));
;     rb1[i] = *(const u32x4*)(bg + (bo + (unsigned)i * 32u * (unsigned)ldb));
;   }
;   const int nk = K >> 6;
;   const int wofs = (tid >> 3) * LSTR + (tid & 7) * 8;
; DI void phase_gemm_plain(const h16* A, int lda, const h16* Bt, int K, h16* C, int ldc, int mt0, int mt1, int ntn, char* smem) {
;   const int Mx = (mt1 - mt0) >> 3;
;   XCD_LOOP(Mx, ntn) {
;     int mt_, nt_;
;     tile_map(u_, Mx, ntn, xcd_, mt_, nt_);
;     const int m0 = (mt0 + mt_) * 128, n0 = nt_ * 128;
;     f32x16 acc[2][2];
;     zero_acc(acc);
;     gemm_tile_deep(A + (size_t)m0 * lda, lda, Bt + (size_t)n0 * K, K, K, acc, (h16*)smem);
.LBB0_58:
	s_ashr_i32 s8, s15, 31
	s_lshr_b32 s8, s8, 26
	s_add_i32 s8, s15, s8
	s_ashr_i32 s9, s8, 6
	s_lshl_b32 s9, s9, 3
	s_sub_i32 s10, s20, s9
	s_min_i32 s10, s10, 8
	s_abs_i32 s11, s10
	v_cvt_f32_u32_e32 v0, s11
	s_sub_i32 s23, 0, s11
	s_andn2_b32 s8, s8, 63
	s_sub_i32 s8, s15, s8
	v_rcp_iflag_f32_e32 v0, v0
	s_abs_i32 s12, s8
	s_xor_b32 s13, s8, s10
	s_ashr_i32 s13, s13, 31
	v_mul_f32_e32 v0, 0x4f7ffffe, v0
	v_cvt_u32_f32_e32 v0, v0
	v_mov_b32_e32 v18, v203
	v_mov_b32_e32 v7, v1
	v_readfirstlane_b32 s24, v0
	s_mul_i32 s23, s23, s24
	s_mul_hi_u32 s23, s24, s23
	s_add_i32 s24, s24, s23
	s_mul_hi_u32 s23, s12, s24
	s_mul_i32 s24, s23, s11
	s_sub_i32 s12, s12, s24
	s_add_i32 s25, s23, 1
	s_sub_i32 s24, s12, s11
	s_cmp_ge_u32 s12, s11
	s_cselect_b32 s23, s25, s23
	s_cselect_b32 s12, s24, s12
	s_add_i32 s24, s23, 1
	s_cmp_ge_u32 s12, s11
	s_cselect_b32 s11, s24, s23
	s_xor_b32 s11, s11, s13
	s_sub_i32 s12, s11, s13
	s_add_i32 s9, s9, s21
	s_mul_i32 s10, s10, s12
	s_add_i32 s9, s9, s8
	s_sub_i32 s8, s9, s10
	s_lshl_b32 s24, s8, 7
	s_lshl_b32 s23, s12, 7
	s_mul_i32 s8, s8, 0xb0000
	s_mul_hi_i32 s9, s24, 0x1600
	s_add_u32 s10, s18, s8
	s_addc_u32 s11, s19, s9
	s_mul_i32 s12, s12, 0xb0000
	s_add_u32 s8, s16, s12
	v_ashrrev_i32_e32 v19, 3, v18
	s_movk_i32 s12, 0xb00
	v_lshlrev_b32_e32 v2, 3, v18
	v_mul_lo_u32 v0, v19, s12
	v_and_b32_e32 v20, 56, v2
	v_bfe_u32 v21, v18, 4, 3
	v_lshlrev_b32_e32 v21, 3, v21
	v_xor_b32_e32 v20, v20, v21
	v_or_b32_e32 v0, v0, v20
	s_mul_hi_i32 s9, s23, 0x1600
	v_add_u32_e32 v6, 0x42000, v0
	s_addc_u32 s9, s17, s9
	v_add_u32_e32 v2, 0x16000, v0
	v_mov_b32_e32 v3, v1
	v_add_u32_e32 v4, 0x2c000, v0
	v_mov_b32_e32 v5, v1
	s_waitcnt vmcnt(0)
	v_lshlrev_b64 v[146:147], 1, v[6:7]
	v_lshl_add_u64 v[6:7], s[8:9], 0, v[146:147]
	v_lshlrev_b64 v[148:149], 1, v[4:5]
	v_lshlrev_b64 v[150:151], 1, v[2:3]
	v_lshlrev_b64 v[152:153], 1, v[0:1]
	v_lshl_add_u64 v[8:9], s[10:11], 0, v[146:147]
	v_lshl_add_u64 v[4:5], s[8:9], 0, v[148:149]
	v_lshl_add_u64 v[10:11], s[10:11], 0, v[148:149]
	v_lshl_add_u64 v[2:3], s[8:9], 0, v[150:151]
	v_lshl_add_u64 v[12:13], s[10:11], 0, v[150:151]
	v_lshl_add_u64 v[14:15], s[8:9], 0, v[152:153]
	v_lshl_add_u64 v[16:17], s[10:11], 0, v[152:153]
	v_readfirstlane_b32 s38, v203
	s_nop 3
	s_lshr_b32 s38, s38, 6
	s_lshl_b32 s38, s38, 10
	v_and_b32_e32 v140, 31, v203
	v_bfe_u32 v141, v203, 5, 1
	v_bfe_u32 v142, v203, 1, 3
	v_xor_b32_e32 v141, v141, v142
	v_lshlrev_b32_e32 v141, 4, v141
	v_lshl_or_b32 v140, v140, 7, v141
	v_lshrrev_b32_e32 v142, 7, v203
	v_lshl_add_u32 v130, v142, 13, v140
	v_bfe_u32 v142, v203, 6, 1
	v_lshl_add_u32 v134, v142, 13, v140
	v_xor_b32_e32 v131, 0x20, v130
	v_xor_b32_e32 v135, 0x20, v134
	v_xor_b32_e32 v132, 0x40, v130
	v_xor_b32_e32 v136, 0x40, v134
	v_xor_b32_e32 v133, 0x60, v130
	v_xor_b32_e32 v137, 0x60, v134
	s_add_u32 m0, s38, 0x0
	s_nop 0
	global_load_lds_dwordx4 v152, s[10:11]
	s_add_u32 m0, s38, 0x4000
	s_nop 0
	global_load_lds_dwordx4 v152, s[8:9]
	s_add_u32 m0, s38, 0x1000
	s_nop 0
	global_load_lds_dwordx4 v150, s[10:11]
	s_add_u32 m0, s38, 0x5000
	s_nop 0
	global_load_lds_dwordx4 v150, s[8:9]
	s_add_u32 m0, s38, 0x2000
	s_nop 0
	global_load_lds_dwordx4 v148, s[10:11]
	s_add_u32 m0, s38, 0x6000
	s_nop 0
	global_load_lds_dwordx4 v148, s[8:9]
	s_add_u32 m0, s38, 0x3000
	s_nop 0
	global_load_lds_dwordx4 v146, s[10:11]
	s_add_u32 m0, s38, 0x7000
	s_nop 0
	global_load_lds_dwordx4 v146, s[8:9]
	s_add_u32 s8, s8, 0x80
	s_addc_u32 s9, s9, 0
	s_add_u32 s10, s10, 0x80
	s_addc_u32 s11, s11, 0
	v_mov_b32_e32 v2, 0
	s_mov_b32 s22, 0
	v_mov_b32_e32 v3, v2
	v_mov_b32_e32 v4, v2
	v_mov_b32_e32 v5, v2
	v_mov_b32_e32 v6, v2
	v_mov_b32_e32 v7, v2
	v_mov_b32_e32 v8, v2
	v_mov_b32_e32 v9, v2
	v_mov_b32_e32 v10, v2
	v_mov_b32_e32 v11, v2
	v_mov_b32_e32 v12, v2
	v_mov_b32_e32 v13, v2
	v_mov_b32_e32 v14, v2
	v_mov_b32_e32 v15, v2
	v_mov_b32_e32 v16, v2
	v_mov_b32_e32 v17, v2
	v_mov_b32_e32 v18, v2
	v_mov_b32_e32 v19, v2
	v_mov_b32_e32 v20, v2
	v_mov_b32_e32 v21, v2
	v_mov_b32_e32 v22, v2
	v_mov_b32_e32 v23, v2
	v_mov_b32_e32 v24, v2
	v_mov_b32_e32 v25, v2
	v_mov_b32_e32 v26, v2
	v_mov_b32_e32 v27, v2
	v_mov_b32_e32 v28, v2
	v_mov_b32_e32 v29, v2
	v_mov_b32_e32 v30, v2
	v_mov_b32_e32 v31, v2
	v_mov_b32_e32 v32, v2
	v_mov_b32_e32 v33, v2
	v_mov_b32_e32 v34, v2
	v_mov_b32_e32 v35, v2
	v_mov_b32_e32 v36, v2
	v_mov_b32_e32 v37, v2
	v_mov_b32_e32 v38, v2
	v_mov_b32_e32 v39, v2
	v_mov_b32_e32 v40, v2
	v_mov_b32_e32 v41, v2
	v_mov_b32_e32 v42, v2
	v_mov_b32_e32 v43, v2
	v_mov_b32_e32 v44, v2
	v_mov_b32_e32 v45, v2
	v_mov_b32_e32 v46, v2
	v_mov_b32_e32 v47, v2
	v_mov_b32_e32 v48, v2
	v_mov_b32_e32 v49, v2
	v_mov_b32_e32 v50, v2
	v_mov_b32_e32 v51, v2
	v_mov_b32_e32 v52, v2
	v_mov_b32_e32 v53, v2
	v_mov_b32_e32 v54, v2
	v_mov_b32_e32 v55, v2
	v_mov_b32_e32 v56, v2
	v_mov_b32_e32 v57, v2
	v_mov_b32_e32 v58, v2
	v_mov_b32_e32 v59, v2
	v_mov_b32_e32 v60, v2
	v_mov_b32_e32 v61, v2
	v_mov_b32_e32 v62, v2
	v_mov_b32_e32 v63, v2
	v_mov_b32_e32 v64, v2
	v_mov_b32_e32 v65, v2
	s_waitcnt vmcnt(0)
	s_barrier
	ds_read_b128 v[66:69], v130 offset:0
	ds_read_b128 v[74:77], v134 offset:16384
	ds_read_b128 v[78:81], v134 offset:20480
	ds_read_b128 v[70:73], v130 offset:4096
	ds_read_b128 v[82:85], v131 offset:0
	ds_read_b128 v[90:93], v135 offset:16384
	ds_read_b128 v[94:97], v135 offset:20480
	ds_read_b128 v[86:89], v131 offset:4096
.Lf2_stage0:
	s_cmp_ge_u32 s22, 43
	s_cbranch_scc1 .Lf2_nl0
	s_waitcnt lgkmcnt(6)
	s_add_u32 m0, s38, 0x8000
	v_mfma_f32_32x32x16_f16 v[50:65], v[66:69], v[74:77], v[50:65]
	global_load_lds_dwordx4 v152, s[10:11]
	ds_read_b128 v[98:101], v132 offset:0
	s_waitcnt lgkmcnt(6)
	s_add_u32 m0, s38, 0xc000
	v_mfma_f32_32x32x16_f16 v[34:49], v[66:69], v[78:81], v[34:49]
	global_load_lds_dwordx4 v152, s[8:9]
	ds_read_b128 v[106:109], v136 offset:16384
	s_waitcnt lgkmcnt(6)
	s_add_u32 m0, s38, 0x9000
	v_mfma_f32_32x32x16_f16 v[18:33], v[70:73], v[74:77], v[18:33]
	global_load_lds_dwordx4 v150, s[10:11]
	ds_read_b128 v[110:113], v136 offset:20480
	s_add_u32 m0, s38, 0xd000
	v_mfma_f32_32x32x16_f16 v[2:17], v[70:73], v[78:81], v[2:17]
	global_load_lds_dwordx4 v150, s[8:9]
	ds_read_b128 v[102:105], v132 offset:4096
	s_waitcnt lgkmcnt(6)
	s_add_u32 m0, s38, 0xa000
	v_mfma_f32_32x32x16_f16 v[50:65], v[82:85], v[90:93], v[50:65]
	global_load_lds_dwordx4 v148, s[10:11]
	ds_read_b128 v[114:117], v133 offset:0
	s_waitcnt lgkmcnt(6)
	s_add_u32 m0, s38, 0xe000
	v_mfma_f32_32x32x16_f16 v[34:49], v[82:85], v[94:97], v[34:49]
	global_load_lds_dwordx4 v148, s[8:9]
	ds_read_b128 v[122:125], v137 offset:16384
	s_waitcnt lgkmcnt(6)
	s_add_u32 m0, s38, 0xb000
	v_mfma_f32_32x32x16_f16 v[18:33], v[86:89], v[90:93], v[18:33]
	global_load_lds_dwordx4 v146, s[10:11]
	ds_read_b128 v[126:129], v137 offset:20480
	s_add_u32 m0, s38, 0xf000
	v_mfma_f32_32x32x16_f16 v[2:17], v[86:89], v[94:97], v[2:17]
	global_load_lds_dwordx4 v146, s[8:9]
	ds_read_b128 v[118:121], v133 offset:4096
	s_add_u32 s8, s8, 0x80
	s_addc_u32 s9, s9, 0
	s_add_u32 s10, s10, 0x80
	s_addc_u32 s11, s11, 0
	s_branch .Lf2_dd0

.Lf2_dd0:
	s_waitcnt lgkmcnt(6)
	v_mfma_f32_32x32x16_f16 v[50:65], v[98:101], v[106:109], v[50:65]
	s_waitcnt lgkmcnt(5)
	v_mfma_f32_32x32x16_f16 v[34:49], v[98:101], v[110:113], v[34:49]
	s_waitcnt lgkmcnt(4)
	v_mfma_f32_32x32x16_f16 v[18:33], v[102:105], v[106:109], v[18:33]
	v_mfma_f32_32x32x16_f16 v[2:17], v[102:105], v[110:113], v[2:17]
	s_waitcnt lgkmcnt(0)
	s_add_i32 s22, s22, 1
	s_waitcnt vmcnt(0)
	s_barrier
	ds_read_b128 v[66:69], v130 offset:32768
	ds_read_b128 v[74:77], v134 offset:49152
	ds_read_b128 v[78:81], v134 offset:53248
	ds_read_b128 v[70:73], v130 offset:36864
	ds_read_b128 v[82:85], v131 offset:32768
	ds_read_b128 v[90:93], v135 offset:49152
	ds_read_b128 v[94:97], v135 offset:53248
	ds_read_b128 v[86:89], v131 offset:36864
	v_mfma_f32_32x32x16_f16 v[50:65], v[114:117], v[122:125], v[50:65]
	v_mfma_f32_32x32x16_f16 v[34:49], v[114:117], v[126:129], v[34:49]
	v_mfma_f32_32x32x16_f16 v[18:33], v[118:121], v[122:125], v[18:33]
	v_mfma_f32_32x32x16_f16 v[2:17], v[118:121], v[126:129], v[2:17]
.Lf2_stage1:
	s_cmp_ge_u32 s22, 43
	s_cbranch_scc1 .Lf2_nl1
	s_waitcnt lgkmcnt(6)
	s_add_u32 m0, s38, 0x0
	v_mfma_f32_32x32x16_f16 v[50:65], v[66:69], v[74:77], v[50:65]
	global_load_lds_dwordx4 v152, s[10:11]
	ds_read_b128 v[98:101], v132 offset:32768
	s_waitcnt lgkmcnt(6)
	s_add_u32 m0, s38, 0x4000
	v_mfma_f32_32x32x16_f16 v[34:49], v[66:69], v[78:81], v[34:49]
	global_load_lds_dwordx4 v152, s[8:9]
	ds_read_b128 v[106:109], v136 offset:49152
	s_waitcnt lgkmcnt(6)
	s_add_u32 m0, s38, 0x1000
	v_mfma_f32_32x32x16_f16 v[18:33], v[70:73], v[74:77], v[18:33]
	global_load_lds_dwordx4 v150, s[10:11]
	ds_read_b128 v[110:113], v136 offset:53248
	s_add_u32 m0, s38, 0x5000
	v_mfma_f32_32x32x16_f16 v[2:17], v[70:73], v[78:81], v[2:17]
	global_load_lds_dwordx4 v150, s[8:9]
	ds_read_b128 v[102:105], v132 offset:36864
	s_waitcnt lgkmcnt(6)
	s_add_u32 m0, s38, 0x2000
	v_mfma_f32_32x32x16_f16 v[50:65], v[82:85], v[90:93], v[50:65]
	global_load_lds_dwordx4 v148, s[10:11]
	ds_read_b128 v[114:117], v133 offset:32768
	s_waitcnt lgkmcnt(6)
	s_add_u32 m0, s38, 0x6000
	v_mfma_f32_32x32x16_f16 v[34:49], v[82:85], v[94:97], v[34:49]
	global_load_lds_dwordx4 v148, s[8:9]
	ds_read_b128 v[122:125], v137 offset:49152
	s_waitcnt lgkmcnt(6)
	s_add_u32 m0, s38, 0x3000
	v_mfma_f32_32x32x16_f16 v[18:33], v[86:89], v[90:93], v[18:33]
	global_load_lds_dwordx4 v146, s[10:11]
	ds_read_b128 v[126:129], v137 offset:53248
	s_add_u32 m0, s38, 0x7000
	v_mfma_f32_32x32x16_f16 v[2:17], v[86:89], v[94:97], v[2:17]
	global_load_lds_dwordx4 v146, s[8:9]
	ds_read_b128 v[118:121], v133 offset:36864
	s_add_u32 s8, s8, 0x80
	s_addc_u32 s9, s9, 0
	s_add_u32 s10, s10, 0x80
	s_addc_u32 s11, s11, 0
	s_branch .Lf2_dd1

; DI void gemm_tile_deep(const h16* __restrict__ A, int lda, const h16* __restrict__ B, int ldb, int K, f32x16 (&acc)[2][2], h16* sm) {
;     ...
;   for (int kt = 0; kt < nk; kt += 2) {
;     DEEP_HALF(ra0, rb0, 0, kt)
;     DEEP_HALF(ra1, rb1, 1, kt + 1)
;   }
.Lf2_dd1:
	s_waitcnt lgkmcnt(6)
	v_mfma_f32_32x32x16_f16 v[50:65], v[98:101], v[106:109], v[50:65]
	s_waitcnt lgkmcnt(5)
	v_mfma_f32_32x32x16_f16 v[34:49], v[98:101], v[110:113], v[34:49]
	s_waitcnt lgkmcnt(4)
	v_mfma_f32_32x32x16_f16 v[18:33], v[102:105], v[106:109], v[18:33]
	v_mfma_f32_32x32x16_f16 v[2:17], v[102:105], v[110:113], v[2:17]
	s_waitcnt lgkmcnt(0)
	s_add_i32 s22, s22, 1
	s_cmp_ge_u32 s22, 44
	s_cbranch_scc1 .Lf2_fin
	s_waitcnt vmcnt(0)
	s_barrier
	ds_read_b128 v[66:69], v130 offset:0
	ds_read_b128 v[74:77], v134 offset:16384
	ds_read_b128 v[78:81], v134 offset:20480
	ds_read_b128 v[70:73], v130 offset:4096
	ds_read_b128 v[82:85], v131 offset:0
	ds_read_b128 v[90:93], v135 offset:16384
	ds_read_b128 v[94:97], v135 offset:20480
	ds_read_b128 v[86:89], v131 offset:4096
	v_mfma_f32_32x32x16_f16 v[50:65], v[114:117], v[122:125], v[50:65]
	v_mfma_f32_32x32x16_f16 v[34:49], v[114:117], v[126:129], v[34:49]
	v_mfma_f32_32x32x16_f16 v[18:33], v[118:121], v[122:125], v[18:33]
	v_mfma_f32_32x32x16_f16 v[2:17], v[118:121], v[126:129], v[2:17]
	s_branch .Lf2_stage0
.Lf2_fin:
	v_mfma_f32_32x32x16_f16 v[50:65], v[114:117], v[122:125], v[50:65]
	v_mfma_f32_32x32x16_f16 v[34:49], v[114:117], v[126:129], v[34:49]
	v_mfma_f32_32x32x16_f16 v[18:33], v[118:121], v[122:125], v[18:33]
	v_mfma_f32_32x32x16_f16 v[2:17], v[118:121], v[126:129], v[2:17]
	s_branch .LBB0_57

; DI int TIDX() { int t = threadIdx.x; asm volatile("" : "+v"(t)); return t; }
; #define XCD_LOOP_W(Mt, ntn) const int xcd_ = BIDX() & 7; const int Mx_ = ((Mt) + 7) >> 3; for (int u_ = BIDX() >> 3; u_ < Mx_ * (ntn); u_ += (int)(gridDim.x >> 3))
; template <class BR>
; DI void gemm_tile_w(const h16* __restrict__ A, int lda, const h16* __restrict__ B, int ldb, BR brow, int K, f32x16 (&acc)[4][2], h16* sm) {
;   const int tid = TIDX(), lane = tid & 63, w = tid >> 6, wm = w >> 1, wn = w & 1, r = lane & 31, hh = lane >> 5;
;   const unsigned ao = (unsigned)(tid >> 2) * (unsigned)lda + (unsigned)(tid & 3) * 8u;
;   const unsigned bo0 = (unsigned)brow(tid >> 2) * (unsigned)ldb + (unsigned)(tid & 3) * 8u;
;   const unsigned bo1 = (unsigned)brow((tid >> 2) + 64) * (unsigned)ldb + (unsigned)(tid & 3) * 8u;
;   const h16* ag = A;
;   const h16* bg = B;
;   u32x4 ra0[4], rb0[2], ra1[4], rb1[2];
; #pragma unroll
;   for (int i = 0; i < 4; ++i) ra0[i] = *(const u32x4*)(ag + (ao + (unsigned)i * 64u * (unsigned)lda));
;   rb0[0] = *(const u32x4*)(bg + bo0);
;   rb0[1] = *(const u32x4*)(bg + bo1);
;   ag += 32; bg += 32;
; #pragma unroll
;   for (int i = 0; i < 4; ++i) ra1[i] = *(const u32x4*)(ag + (ao + (unsigned)i * 64u * (unsigned)lda));
;   rb1[0] = *(const u32x4*)(bg + bo0);
;   rb1[1] = *(const u32x4*)(bg + bo1);
;   const int nk = K >> 5;
;   const int wofs = (tid >> 2) * LS2 + (tid & 3) * 8;
; DI void phase_ffn1(const P& p, int l, int hf, char* smem) {
;     ...
;   XCD_LOOP_W(Mt, 44) {
;     int mt_, nt_;
;     tile_map(u_, Mx_, 44, xcd_, mt_, nt_);
;     if (mt_ >= Mt) continue;
;     const int m0 = mt0 * 128 + mt_ * 256, c0 = nt_ * 64;
;     f32x16 acc[4][2];
;     zero_acc_w(acc);
;     gemm_tile_w(h2 + (size_t)m0 * 1024, 1024, W, 1024,
;                 [&](int rr) { const int q = rr & 63; return ((q >> 5) ? 2816 : 0) + c0 + (rr >> 6) * 32 + (q & 31); }, 1024, acc, (h16*)smem);
.LBB0_71:
	s_mul_hi_i32 s12, s22, 0x2e8ba2e9
	s_lshr_b32 s13, s12, 31
	s_ashr_i32 s12, s12, 6
	s_add_i32 s12, s12, s13
	s_lshl_b32 s14, s12, 3
	s_sub_i32 s13, s21, s14
	s_min_i32 s15, s13, 8
	s_abs_i32 s13, s15
	v_cvt_f32_u32_e32 v0, s13
	s_sub_i32 s18, 0, s13
	s_mulk_i32 s12, 0xfea0
	s_add_i32 s12, s12, s22
	v_rcp_iflag_f32_e32 v0, v0
	s_abs_i32 s16, s12
	s_xor_b32 s17, s12, s15
	s_ashr_i32 s17, s17, 31
	v_mul_f32_e32 v0, 0x4f7ffffe, v0
	v_cvt_u32_f32_e32 v0, v0
	s_nop 0
	v_readfirstlane_b32 s19, v0
	s_mul_i32 s18, s18, s19
	s_mul_hi_u32 s18, s19, s18
	s_add_i32 s19, s19, s18
	s_mul_hi_u32 s18, s16, s19
	s_mul_i32 s19, s18, s13
	s_sub_i32 s16, s16, s19
	s_add_i32 s26, s18, 1
	s_sub_i32 s19, s16, s13
	s_cmp_ge_u32 s16, s13
	s_cselect_b32 s18, s26, s18
	s_cselect_b32 s16, s19, s16
	s_add_i32 s19, s18, 1
	s_cmp_ge_u32 s16, s13
	s_cselect_b32 s13, s19, s18
	s_xor_b32 s13, s13, s17
	s_sub_i32 s13, s13, s17
	s_add_i32 s14, s14, s38
	s_mul_i32 s15, s15, s13
	s_add_i32 s14, s14, s12
	s_sub_i32 s12, s14, s15
	s_cmp_ge_i32 s12, s20
	s_cbranch_scc1 .LBB0_70
	v_mov_b32_e32 v18, v203
	s_lshl_b32 s26, s13, 6
	s_lshl_b32 s12, s12, 8
	v_ashrrev_i32_e32 v19, 2, v18
	v_bfe_i32 v2, v18, 7, 1
	v_and_b32_e32 v2, 0xb00, v2
	v_lshrrev_b32_e32 v3, 3, v18
	v_and_or_b32 v4, v19, 31, s26
	v_and_b32_e32 v3, 0x3fffe0, v3
	v_add_u32_e32 v2, v2, v4
	v_add_u32_e32 v10, v2, v3
	v_add_u32_e32 v3, 64, v19
	s_ashr_i32 s13, s12, 31
	v_lshlrev_b32_e32 v0, 3, v18
	v_lshrrev_b32_e32 v3, 1, v3
	s_lshl_b64 s[14:15], s[12:13], 11
	v_and_b32_e32 v20, 24, v0
	v_bfe_u32 v21, v18, 4, 2
	v_lshlrev_b32_e32 v21, 3, v21
	v_xor_b32_e32 v20, v20, v21
	v_and_b32_e32 v3, 0x3fffe0, v3
	s_add_u32 s14, s24, s14
	v_add_u32_e32 v11, v2, v3
	v_lshl_or_b32 v210, v10, 10, v20
	v_mov_b32_e32 v211, v1
	s_addc_u32 s15, s25, s15
	v_lshl_or_b32 v0, v19, 10, v20
	v_lshl_or_b32 v212, v11, 10, v20
	v_lshlrev_b64 v[10:11], 1, v[210:211]
	v_mov_b32_e32 v213, v1
	v_lshl_add_u64 v[2:3], v[0:1], 1, s[14:15]
	v_add_u32_e32 v204, 0x10000, v0
	v_mov_b32_e32 v205, v1
	v_add_u32_e32 v206, 0x20000, v0
	v_mov_b32_e32 v207, v1
	v_add_u32_e32 v208, 0x30000, v0
	v_mov_b32_e32 v209, v1
	v_lshl_add_u64 v[12:13], s[6:7], 0, v[10:11]
	v_lshlrev_b64 v[14:15], 1, v[212:213]
	v_lshl_add_u64 v[4:5], v[204:205], 1, s[14:15]
	v_lshl_add_u64 v[6:7], v[206:207], 1, s[14:15]
	v_lshl_add_u64 v[8:9], v[208:209], 1, s[14:15]
	v_lshl_add_u64 v[16:17], s[6:7], 0, v[14:15]
	v_readfirstlane_b32 s18, v203
	s_nop 3
	s_lshr_b32 s18, s18, 6
	s_lshl_b32 s18, s18, 10
	v_and_b32_e32 v136, 31, v203
	v_bfe_u32 v137, v203, 5, 1
	v_bfe_u32 v138, v203, 2, 2
	v_xor_b32_e32 v137, v137, v138
	v_lshlrev_b32_e32 v137, 4, v137
	v_lshl_or_b32 v136, v136, 6, v137
	v_lshrrev_b32_e32 v138, 7, v203
	v_lshl_add_u32 v130, v138, 13, v136
	v_bfe_u32 v138, v203, 6, 1
	v_lshl_add_u32 v132, v138, 12, v136
	v_xor_b32_e32 v131, 32, v130
	v_xor_b32_e32 v133, 32, v132
	v_lshlrev_b32_e32 v139, 1, v0
	v_lshlrev_b32_e32 v140, 1, v204
	v_lshlrev_b32_e32 v141, 1, v206
	v_lshlrev_b32_e32 v142, 1, v208
	v_lshlrev_b32_e32 v143, 1, v210
	v_lshlrev_b32_e32 v144, 1, v212
	s_mov_b64 s[16:17], s[6:7]
	s_add_u32 m0, s18, 0x0
	s_nop 0
	global_load_lds_dwordx4 v139, s[14:15]
	s_add_u32 m0, s18, 0x1000
	s_nop 0
	global_load_lds_dwordx4 v140, s[14:15]
	s_add_u32 m0, s18, 0x2000
	s_nop 0
	global_load_lds_dwordx4 v141, s[14:15]
	s_add_u32 m0, s18, 0x3000
	s_nop 0
	global_load_lds_dwordx4 v142, s[14:15]
	s_add_u32 m0, s18, 0x4000
	s_nop 0
	global_load_lds_dwordx4 v143, s[16:17]
	s_add_u32 m0, s18, 0x5000
	s_nop 0
	global_load_lds_dwordx4 v144, s[16:17]
	s_add_u32 s14, s14, 64
	s_addc_u32 s15, s15, 0
	s_add_u32 s16, s16, 64
	s_addc_u32 s17, s17, 0
	v_mov_b32_e32 v2, 0
	s_mov_b32 s13, 0
	v_mov_b32_e32 v3, v2
	v_mov_b32_e32 v4, v2
	v_mov_b32_e32 v5, v2
	v_mov_b32_e32 v6, v2
	v_mov_b32_e32 v7, v2
	v_mov_b32_e32 v8, v2
	v_mov_b32_e32 v9, v2
	v_mov_b32_e32 v10, v2
	v_mov_b32_e32 v11, v2
	v_mov_b32_e32 v12, v2
	v_mov_b32_e32 v13, v2
	v_mov_b32_e32 v14, v2
	v_mov_b32_e32 v15, v2
	v_mov_b32_e32 v16, v2
	v_mov_b32_e32 v17, v2
	v_mov_b32_e32 v18, v2
	v_mov_b32_e32 v19, v2
	v_mov_b32_e32 v20, v2
	v_mov_b32_e32 v21, v2
	v_mov_b32_e32 v22, v2
	v_mov_b32_e32 v23, v2
	v_mov_b32_e32 v24, v2
	v_mov_b32_e32 v25, v2
	v_mov_b32_e32 v26, v2
	v_mov_b32_e32 v27, v2
	v_mov_b32_e32 v28, v2
	v_mov_b32_e32 v29, v2
	v_mov_b32_e32 v30, v2
	v_mov_b32_e32 v31, v2
	v_mov_b32_e32 v32, v2
	v_mov_b32_e32 v33, v2
	v_mov_b32_e32 v34, v2
	v_mov_b32_e32 v35, v2
	v_mov_b32_e32 v36, v2
	v_mov_b32_e32 v37, v2
	v_mov_b32_e32 v38, v2
	v_mov_b32_e32 v39, v2
	v_mov_b32_e32 v40, v2
	v_mov_b32_e32 v41, v2
	v_mov_b32_e32 v42, v2
	v_mov_b32_e32 v43, v2
	v_mov_b32_e32 v44, v2
	v_mov_b32_e32 v45, v2
	v_mov_b32_e32 v46, v2
	v_mov_b32_e32 v47, v2
	v_mov_b32_e32 v48, v2
	v_mov_b32_e32 v49, v2
	s_waitcnt vmcnt(15)
	v_mov_b32_e32 v50, v2
	v_mov_b32_e32 v51, v2
	v_mov_b32_e32 v52, v2
	v_mov_b32_e32 v53, v2
	s_waitcnt vmcnt(14)
	v_mov_b32_e32 v54, v2
	v_mov_b32_e32 v55, v2
	v_mov_b32_e32 v56, v2
	v_mov_b32_e32 v57, v2
	s_waitcnt vmcnt(13)
	v_mov_b32_e32 v58, v2
	v_mov_b32_e32 v59, v2
	v_mov_b32_e32 v60, v2
	v_mov_b32_e32 v61, v2
	s_waitcnt vmcnt(12)
	v_mov_b32_e32 v62, v2
	v_mov_b32_e32 v63, v2
	v_mov_b32_e32 v64, v2
	v_mov_b32_e32 v65, v2
	v_mov_b32_e32 v66, v2
	v_mov_b32_e32 v67, v2
	v_mov_b32_e32 v68, v2
	v_mov_b32_e32 v69, v2
	v_mov_b32_e32 v70, v2
	v_mov_b32_e32 v71, v2
	v_mov_b32_e32 v72, v2
	v_mov_b32_e32 v73, v2
	v_mov_b32_e32 v74, v2
	v_mov_b32_e32 v75, v2
	v_mov_b32_e32 v76, v2
	v_mov_b32_e32 v77, v2
	v_mov_b32_e32 v78, v2
	v_mov_b32_e32 v79, v2
	v_mov_b32_e32 v80, v2
	v_mov_b32_e32 v81, v2
	v_mov_b32_e32 v82, v2
	v_mov_b32_e32 v83, v2
	v_mov_b32_e32 v84, v2
	v_mov_b32_e32 v85, v2
	v_mov_b32_e32 v86, v2
	v_mov_b32_e32 v87, v2
	v_mov_b32_e32 v88, v2
	v_mov_b32_e32 v89, v2
	v_mov_b32_e32 v90, v2
	v_mov_b32_e32 v91, v2
	v_mov_b32_e32 v92, v2
	v_mov_b32_e32 v93, v2
	v_mov_b32_e32 v94, v2
	v_mov_b32_e32 v95, v2
	v_mov_b32_e32 v96, v2
	v_mov_b32_e32 v97, v2
	v_mov_b32_e32 v98, v2
	v_mov_b32_e32 v99, v2
	v_mov_b32_e32 v100, v2
	v_mov_b32_e32 v101, v2
	v_mov_b32_e32 v102, v2
	v_mov_b32_e32 v103, v2
	v_mov_b32_e32 v104, v2
	v_mov_b32_e32 v105, v2
	v_mov_b32_e32 v106, v2
	v_mov_b32_e32 v107, v2
	v_mov_b32_e32 v108, v2
	v_mov_b32_e32 v109, v2
	v_mov_b32_e32 v110, v2
	v_mov_b32_e32 v111, v2
	v_mov_b32_e32 v112, v2
	v_mov_b32_e32 v113, v2
	v_mov_b32_e32 v114, v2
	v_mov_b32_e32 v115, v2
	v_mov_b32_e32 v116, v2
	v_mov_b32_e32 v117, v2
	v_mov_b32_e32 v118, v2
	v_mov_b32_e32 v119, v2
	v_mov_b32_e32 v120, v2
	v_mov_b32_e32 v121, v2
	v_mov_b32_e32 v122, v2
	v_mov_b32_e32 v123, v2
	v_mov_b32_e32 v124, v2
	v_mov_b32_e32 v125, v2
	v_mov_b32_e32 v126, v2
	v_mov_b32_e32 v127, v2
	v_mov_b32_e32 v128, v2
	v_mov_b32_e32 v129, v2
	s_waitcnt vmcnt(0)
	s_barrier
	ds_read_b128 v[178:181], v130 offset:0
	ds_read_b128 v[194:197], v132 offset:16384
	ds_read_b128 v[198:201], v132 offset:18432
	ds_read_b128 v[182:185], v130 offset:2048
	ds_read_b128 v[186:189], v130 offset:4096
	ds_read_b128 v[190:193], v130 offset:6144
.Lfg_stage0:
	s_cmp_ge_u32 s13, 31
	s_cbranch_scc1 .Lfg_nl0
	s_waitcnt lgkmcnt(4)
	v_mfma_f32_32x32x16_f16 v[114:129], v[178:181], v[194:197], v[114:129]
	ds_read_b128 v[216:219], v131 offset:0
	s_waitcnt lgkmcnt(4)
	s_add_u32 m0, s18, 0x6000
	v_mfma_f32_32x32x16_f16 v[98:113], v[178:181], v[198:201], v[98:113]
	global_load_lds_dwordx4 v139, s[14:15]
	ds_read_b128 v[234:237], v133 offset:16384
	s_waitcnt lgkmcnt(4)
	s_add_u32 m0, s18, 0x7000
	v_mfma_f32_32x32x16_f16 v[82:97], v[182:185], v[194:197], v[82:97]
	global_load_lds_dwordx4 v140, s[14:15]
	ds_read_b128 v[240:243], v133 offset:18432
	s_add_u32 m0, s18, 0x8000
	v_mfma_f32_32x32x16_f16 v[66:81], v[182:185], v[198:201], v[66:81]
	global_load_lds_dwordx4 v141, s[14:15]
	ds_read_b128 v[220:223], v131 offset:2048
	s_waitcnt lgkmcnt(5)
	s_add_u32 m0, s18, 0x9000
	v_mfma_f32_32x32x16_f16 v[50:65], v[186:189], v[194:197], v[50:65]
	global_load_lds_dwordx4 v142, s[14:15]
	ds_read_b128 v[226:229], v131 offset:4096
	s_add_u32 m0, s18, 0xa000
	v_mfma_f32_32x32x16_f16 v[34:49], v[186:189], v[198:201], v[34:49]
	global_load_lds_dwordx4 v143, s[16:17]
	ds_read_b128 v[230:233], v131 offset:6144
	s_waitcnt lgkmcnt(6)
	s_add_u32 m0, s18, 0xb000
	v_mfma_f32_32x32x16_f16 v[18:33], v[190:193], v[194:197], v[18:33]
	global_load_lds_dwordx4 v144, s[16:17]
	v_mfma_f32_32x32x16_f16 v[2:17], v[190:193], v[198:201], v[2:17]
	s_add_u32 s14, s14, 64
	s_addc_u32 s15, s15, 0
	s_add_u32 s16, s16, 64
	s_addc_u32 s17, s17, 0
	s_branch .Lfg_dd0

; template <class BR>
; DI void gemm_tile_w(const h16* __restrict__ A, int lda, const h16* __restrict__ B, int ldb, BR brow, int K, f32x16 (&acc)[4][2], h16* sm) {
;     ...
;   for (int kt = 0; kt < nk; kt += 2) {
;     WIDE_HALF(ra0, rb0, 0, kt)
;     WIDE_HALF(ra1, rb1, 1, kt + 1)
.Lfg_dd0:
	s_waitcnt lgkmcnt(4)
	v_mfma_f32_32x32x16_f16 v[114:129], v[216:219], v[234:237], v[114:129]
	s_waitcnt lgkmcnt(3)
	v_mfma_f32_32x32x16_f16 v[98:113], v[216:219], v[240:243], v[98:113]
	s_waitcnt lgkmcnt(2)
	v_mfma_f32_32x32x16_f16 v[82:97], v[220:223], v[234:237], v[82:97]
	v_mfma_f32_32x32x16_f16 v[66:81], v[220:223], v[240:243], v[66:81]
	s_waitcnt lgkmcnt(0)
	s_add_i32 s13, s13, 1
	s_waitcnt vmcnt(0)
	s_barrier
	ds_read_b128 v[178:181], v130 offset:24576
	ds_read_b128 v[194:197], v132 offset:40960
	ds_read_b128 v[198:201], v132 offset:43008
	ds_read_b128 v[182:185], v130 offset:26624
	ds_read_b128 v[186:189], v130 offset:28672
	ds_read_b128 v[190:193], v130 offset:30720
	v_mfma_f32_32x32x16_f16 v[50:65], v[226:229], v[234:237], v[50:65]
	v_mfma_f32_32x32x16_f16 v[34:49], v[226:229], v[240:243], v[34:49]
	v_mfma_f32_32x32x16_f16 v[18:33], v[230:233], v[234:237], v[18:33]
	v_mfma_f32_32x32x16_f16 v[2:17], v[230:233], v[240:243], v[2:17]
.Lfg_stage1:
	s_cmp_ge_u32 s13, 31
	s_cbranch_scc1 .Lfg_nl1
	s_waitcnt lgkmcnt(4)
	v_mfma_f32_32x32x16_f16 v[114:129], v[178:181], v[194:197], v[114:129]
	ds_read_b128 v[216:219], v131 offset:24576
	s_waitcnt lgkmcnt(4)
	s_add_u32 m0, s18, 0x0
	v_mfma_f32_32x32x16_f16 v[98:113], v[178:181], v[198:201], v[98:113]
	global_load_lds_dwordx4 v139, s[14:15]
	ds_read_b128 v[234:237], v133 offset:40960
	s_waitcnt lgkmcnt(4)
	s_add_u32 m0, s18, 0x1000
	v_mfma_f32_32x32x16_f16 v[82:97], v[182:185], v[194:197], v[82:97]
	global_load_lds_dwordx4 v140, s[14:15]
	ds_read_b128 v[240:243], v133 offset:43008
	s_add_u32 m0, s18, 0x2000
	v_mfma_f32_32x32x16_f16 v[66:81], v[182:185], v[198:201], v[66:81]
	global_load_lds_dwordx4 v141, s[14:15]
	ds_read_b128 v[220:223], v131 offset:26624
	s_waitcnt lgkmcnt(5)
	s_add_u32 m0, s18, 0x3000
	v_mfma_f32_32x32x16_f16 v[50:65], v[186:189], v[194:197], v[50:65]
	global_load_lds_dwordx4 v142, s[14:15]
	ds_read_b128 v[226:229], v131 offset:28672
	s_add_u32 m0, s18, 0x4000
	v_mfma_f32_32x32x16_f16 v[34:49], v[186:189], v[198:201], v[34:49]
	global_load_lds_dwordx4 v143, s[16:17]
	ds_read_b128 v[230:233], v131 offset:30720
	s_waitcnt lgkmcnt(6)
	s_add_u32 m0, s18, 0x5000
	v_mfma_f32_32x32x16_f16 v[18:33], v[190:193], v[194:197], v[18:33]
	global_load_lds_dwordx4 v144, s[16:17]
	v_mfma_f32_32x32x16_f16 v[2:17], v[190:193], v[198:201], v[2:17]
	s_add_u32 s14, s14, 64
	s_addc_u32 s15, s15, 0
	s_add_u32 s16, s16, 64
	s_addc_u32 s17, s17, 0
	s_branch .Lfg_dd1

; template <class BR>
; DI void gemm_tile_w(const h16* __restrict__ A, int lda, const h16* __restrict__ B, int ldb, BR brow, int K, f32x16 (&acc)[4][2], h16* sm) {
;     ...
;   for (int kt = 0; kt < nk; kt += 2) {
;     WIDE_HALF(ra0, rb0, 0, kt)
;     WIDE_HALF(ra1, rb1, 1, kt + 1)
;   }
;     ...
;   __syncthreads();
.Lfg_dd1:
	s_waitcnt lgkmcnt(4)
	v_mfma_f32_32x32x16_f16 v[114:129], v[216:219], v[234:237], v[114:129]
	s_waitcnt lgkmcnt(3)
	v_mfma_f32_32x32x16_f16 v[98:113], v[216:219], v[240:243], v[98:113]
	s_waitcnt lgkmcnt(2)
	v_mfma_f32_32x32x16_f16 v[82:97], v[220:223], v[234:237], v[82:97]
	v_mfma_f32_32x32x16_f16 v[66:81], v[220:223], v[240:243], v[66:81]
	s_waitcnt lgkmcnt(0)
	s_add_i32 s13, s13, 1
	s_cmp_ge_u32 s13, 32
	s_cbranch_scc1 .Lfg_fin
	s_waitcnt vmcnt(0)
	s_barrier
	ds_read_b128 v[178:181], v130 offset:0
	ds_read_b128 v[194:197], v132 offset:16384
	ds_read_b128 v[198:201], v132 offset:18432
	ds_read_b128 v[182:185], v130 offset:2048
	ds_read_b128 v[186:189], v130 offset:4096
	ds_read_b128 v[190:193], v130 offset:6144
	v_mfma_f32_32x32x16_f16 v[50:65], v[226:229], v[234:237], v[50:65]
	v_mfma_f32_32x32x16_f16 v[34:49], v[226:229], v[240:243], v[34:49]
	v_mfma_f32_32x32x16_f16 v[18:33], v[230:233], v[234:237], v[18:33]
	v_mfma_f32_32x32x16_f16 v[2:17], v[230:233], v[240:243], v[2:17]
	s_branch .Lfg_stage0
.Lfg_fin:
	v_mfma_f32_32x32x16_f16 v[50:65], v[226:229], v[234:237], v[50:65]
	v_mfma_f32_32x32x16_f16 v[34:49], v[226:229], v[240:243], v[34:49]
	v_mfma_f32_32x32x16_f16 v[18:33], v[230:233], v[234:237], v[18:33]
	v_mfma_f32_32x32x16_f16 v[2:17], v[230:233], v[240:243], v[2:17]
	s_branch .LBB0_69

; DI int TIDX() { int t = threadIdx.x; asm volatile("" : "+v"(t)); return t; }
; #define XCD_LOOP(Mx, ntn) const int xcd_ = BIDX() & 7; for (int u_ = BIDX() >> 3; u_ < (Mx) * (ntn); u_ += (int)(gridDim.x >> 3))
; DI void gemm_tile_deep(const h16* __restrict__ A, int lda, const h16* __restrict__ B, int ldb, int K, f32x16 (&acc)[2][2], h16* sm) {
;   const int tid = TIDX(), lane = tid & 63, w = tid >> 6, wm = w >> 1, wn = w & 1, r = lane & 31, hh = lane >> 5;
;   const unsigned ao = (unsigned)(tid >> 3) * (unsigned)lda + (unsigned)(tid & 7) * 8u;
;   const unsigned bo = (unsigned)(tid >> 3) * (unsigned)ldb + (unsigned)(tid & 7) * 8u;
;   const h16* ag = A;
;   const h16* bg = B;
;   u32x4 ra0[4], rb0[4], ra1[4], rb1[4];
; #pragma unroll
;   for (int i = 0; i < 4; ++i) {
;     ra0[i] = *(const u32x4*)(ag + (ao + (unsigned)i * 32u * (unsigned)lda));
;     rb0[i] = *(const u32x4*)(bg + (bo + (unsigned)i * 32u * (unsigned)ldb));
;   }
;   ag += 64; bg += 64;
; #pragma unroll
;   for (int i = 0; i < 4; ++i) {
;     ra1[i] = *(const u32x4*)(ag + (ao + (unsigned)i * 32u * (unsigned)lda));
;     rb1[i] = *(const u32x4*)(bg + (bo + (unsigned)i * 32u * (unsigned)ldb));
;   }
;   const int nk = K >> 6;
;   const int wofs = (tid >> 3) * LSTR + (tid & 7) * 8;
; DI void phase_gemm_plain(const h16* A, int lda, const h16* Bt, int K, h16* C, int ldc, int mt0, int mt1, int ntn, char* smem) {
;   const int Mx = (mt1 - mt0) >> 3;
;   XCD_LOOP(Mx, ntn) {
;     int mt_, nt_;
;     tile_map(u_, Mx, ntn, xcd_, mt_, nt_);
;     const int m0 = (mt0 + mt_) * 128, n0 = nt_ * 128;
;     f32x16 acc[2][2];
;     zero_acc(acc);
;     gemm_tile_deep(A + (size_t)m0 * lda, lda, Bt + (size_t)n0 * K, K, K, acc, (h16*)smem);
.LBB0_91:
	s_ashr_i32 s4, s15, 31
	s_lshr_b32 s4, s4, 26
	s_add_i32 s4, s15, s4
	s_ashr_i32 s5, s4, 6
	s_lshl_b32 s5, s5, 3
	s_sub_i32 s6, s20, s5
	s_min_i32 s6, s6, 8
	s_abs_i32 s7, s6
	v_cvt_f32_u32_e32 v0, s7
	s_sub_i32 s10, 0, s7
	s_andn2_b32 s4, s4, 63
	s_sub_i32 s4, s15, s4
	v_rcp_iflag_f32_e32 v0, v0
	s_abs_i32 s8, s4
	s_xor_b32 s9, s4, s6
	s_ashr_i32 s9, s9, 31
	v_mul_f32_e32 v0, 0x4f7ffffe, v0
	v_cvt_u32_f32_e32 v0, v0
	v_mov_b32_e32 v18, v203
	v_mov_b32_e32 v7, v1
	v_readfirstlane_b32 s11, v0
	s_mul_i32 s10, s10, s11
	s_mul_hi_u32 s10, s11, s10
	s_add_i32 s11, s11, s10
	s_mul_hi_u32 s10, s8, s11
	s_mul_i32 s11, s10, s7
	s_sub_i32 s8, s8, s11
	s_add_i32 s12, s10, 1
	s_sub_i32 s11, s8, s7
	s_cmp_ge_u32 s8, s7
	s_cselect_b32 s10, s12, s10
	s_cselect_b32 s8, s11, s8
	s_add_i32 s11, s10, 1
	s_cmp_ge_u32 s8, s7
	s_cselect_b32 s7, s11, s10
	s_xor_b32 s7, s7, s9
	s_sub_i32 s7, s7, s9
	s_add_i32 s5, s5, s21
	s_mul_i32 s6, s6, s7
	s_add_i32 s5, s5, s4
	s_sub_i32 s4, s5, s6
	s_lshl_b32 s6, s4, 7
	s_lshl_b32 s4, s7, 7
	s_ashr_i32 s7, s6, 31
	s_lshl_b64 s[8:9], s[6:7], 11
	s_add_u32 s10, s16, s8
	v_lshlrev_b32_e32 v0, 3, v18
	s_addc_u32 s11, s17, s9
	s_ashr_i32 s5, s4, 31
	v_ashrrev_i32_e32 v19, 3, v18
	v_and_b32_e32 v20, 56, v0
	v_bfe_u32 v21, v18, 4, 3
	v_lshlrev_b32_e32 v21, 3, v21
	v_xor_b32_e32 v20, v20, v21
	s_lshl_b64 s[8:9], s[4:5], 11
	v_lshl_or_b32 v0, v19, 10, v20
	s_add_u32 s8, s18, s8
	v_add_u32_e32 v6, 0x18000, v0
	s_addc_u32 s9, s19, s9
	v_add_u32_e32 v2, 0x8000, v0
	v_mov_b32_e32 v3, v1
	v_add_u32_e32 v4, 0x10000, v0
	v_mov_b32_e32 v5, v1
	s_waitcnt vmcnt(0)
	v_lshlrev_b64 v[146:147], 1, v[6:7]
	v_lshl_add_u64 v[6:7], s[8:9], 0, v[146:147]
	v_lshlrev_b64 v[148:149], 1, v[4:5]
	v_lshlrev_b64 v[150:151], 1, v[2:3]
	v_lshlrev_b64 v[152:153], 1, v[0:1]
	v_lshl_add_u64 v[8:9], s[10:11], 0, v[146:147]
	v_lshl_add_u64 v[4:5], s[8:9], 0, v[148:149]
	v_lshl_add_u64 v[10:11], s[10:11], 0, v[148:149]
	v_lshl_add_u64 v[2:3], s[8:9], 0, v[150:151]
	v_lshl_add_u64 v[12:13], s[10:11], 0, v[150:151]
	v_lshl_add_u64 v[14:15], s[8:9], 0, v[152:153]
	v_lshl_add_u64 v[16:17], s[10:11], 0, v[152:153]
	v_readfirstlane_b32 s38, v203
	s_nop 3
	s_lshr_b32 s38, s38, 6
	s_lshl_b32 s38, s38, 10
	v_and_b32_e32 v140, 31, v203
	v_bfe_u32 v141, v203, 5, 1
	v_bfe_u32 v142, v203, 1, 3
	v_xor_b32_e32 v141, v141, v142
	v_lshlrev_b32_e32 v141, 4, v141
	v_lshl_or_b32 v140, v140, 7, v141
	v_lshrrev_b32_e32 v142, 7, v203
	v_lshl_add_u32 v130, v142, 13, v140
	v_bfe_u32 v142, v203, 6, 1
	v_lshl_add_u32 v134, v142, 13, v140
	v_xor_b32_e32 v131, 0x20, v130
	v_xor_b32_e32 v135, 0x20, v134
	v_xor_b32_e32 v132, 0x40, v130
	v_xor_b32_e32 v136, 0x40, v134
	v_xor_b32_e32 v133, 0x60, v130
	v_xor_b32_e32 v137, 0x60, v134
	s_add_u32 m0, s38, 0x0
	s_nop 0
	global_load_lds_dwordx4 v152, s[10:11]
	s_add_u32 m0, s38, 0x4000
	s_nop 0
	global_load_lds_dwordx4 v152, s[8:9]
	s_add_u32 m0, s38, 0x1000
	s_nop 0
	global_load_lds_dwordx4 v150, s[10:11]
	s_add_u32 m0, s38, 0x5000
	s_nop 0
	global_load_lds_dwordx4 v150, s[8:9]
	s_add_u32 m0, s38, 0x2000
	s_nop 0
	global_load_lds_dwordx4 v148, s[10:11]
	s_add_u32 m0, s38, 0x6000
	s_nop 0
	global_load_lds_dwordx4 v148, s[8:9]
	s_add_u32 m0, s38, 0x3000
	s_nop 0
	global_load_lds_dwordx4 v146, s[10:11]
	s_add_u32 m0, s38, 0x7000
	s_nop 0
	global_load_lds_dwordx4 v146, s[8:9]
	s_add_u32 s8, s8, 0x80
	s_addc_u32 s9, s9, 0
	s_add_u32 s10, s10, 0x80
	s_addc_u32 s11, s11, 0
	v_mov_b32_e32 v2, 0
	s_mov_b32 s22, 0
	v_mov_b32_e32 v3, v2
	v_mov_b32_e32 v4, v2
	v_mov_b32_e32 v5, v2
	v_mov_b32_e32 v6, v2
	v_mov_b32_e32 v7, v2
	v_mov_b32_e32 v8, v2
	v_mov_b32_e32 v9, v2
	v_mov_b32_e32 v10, v2
	v_mov_b32_e32 v11, v2
	v_mov_b32_e32 v12, v2
	v_mov_b32_e32 v13, v2
	v_mov_b32_e32 v14, v2
	v_mov_b32_e32 v15, v2
	v_mov_b32_e32 v16, v2
	v_mov_b32_e32 v17, v2
	v_mov_b32_e32 v18, v2
	v_mov_b32_e32 v19, v2
	v_mov_b32_e32 v20, v2
	v_mov_b32_e32 v21, v2
	v_mov_b32_e32 v22, v2
	v_mov_b32_e32 v23, v2
	v_mov_b32_e32 v24, v2
	v_mov_b32_e32 v25, v2
	v_mov_b32_e32 v26, v2
	v_mov_b32_e32 v27, v2
	v_mov_b32_e32 v28, v2
	v_mov_b32_e32 v29, v2
	v_mov_b32_e32 v30, v2
	v_mov_b32_e32 v31, v2
	v_mov_b32_e32 v32, v2
	v_mov_b32_e32 v33, v2
	v_mov_b32_e32 v34, v2
	v_mov_b32_e32 v35, v2
	v_mov_b32_e32 v36, v2
	v_mov_b32_e32 v37, v2
	v_mov_b32_e32 v38, v2
	v_mov_b32_e32 v39, v2
	v_mov_b32_e32 v40, v2
	v_mov_b32_e32 v41, v2
	v_mov_b32_e32 v42, v2
	v_mov_b32_e32 v43, v2
	v_mov_b32_e32 v44, v2
	v_mov_b32_e32 v45, v2
	v_mov_b32_e32 v46, v2
	v_mov_b32_e32 v47, v2
	v_mov_b32_e32 v48, v2
	v_mov_b32_e32 v49, v2
	v_mov_b32_e32 v50, v2
	v_mov_b32_e32 v51, v2
	v_mov_b32_e32 v52, v2
	v_mov_b32_e32 v53, v2
	v_mov_b32_e32 v54, v2
	v_mov_b32_e32 v55, v2
	v_mov_b32_e32 v56, v2
	v_mov_b32_e32 v57, v2
	v_mov_b32_e32 v58, v2
	v_mov_b32_e32 v59, v2
	v_mov_b32_e32 v60, v2
	v_mov_b32_e32 v61, v2
	v_mov_b32_e32 v62, v2
	v_mov_b32_e32 v63, v2
	v_mov_b32_e32 v64, v2
	v_mov_b32_e32 v65, v2
	s_waitcnt vmcnt(0)
	s_barrier
	ds_read_b128 v[66:69], v130 offset:0
	ds_read_b128 v[74:77], v134 offset:16384
	ds_read_b128 v[78:81], v134 offset:20480
	ds_read_b128 v[70:73], v130 offset:4096
	ds_read_b128 v[82:85], v131 offset:0
	ds_read_b128 v[90:93], v135 offset:16384
	ds_read_b128 v[94:97], v135 offset:20480
	ds_read_b128 v[86:89], v131 offset:4096
.Lwo_stage0:
	s_cmp_ge_u32 s22, 15
	s_cbranch_scc1 .Lwo_nl0
	s_waitcnt lgkmcnt(6)
	s_add_u32 m0, s38, 0x8000
	v_mfma_f32_32x32x16_f16 v[50:65], v[66:69], v[74:77], v[50:65]
	global_load_lds_dwordx4 v152, s[10:11]
	ds_read_b128 v[98:101], v132 offset:0
	s_waitcnt lgkmcnt(6)
	s_add_u32 m0, s38, 0xc000
	v_mfma_f32_32x32x16_f16 v[34:49], v[66:69], v[78:81], v[34:49]
	global_load_lds_dwordx4 v152, s[8:9]
	ds_read_b128 v[106:109], v136 offset:16384
	s_waitcnt lgkmcnt(6)
	s_add_u32 m0, s38, 0x9000
	v_mfma_f32_32x32x16_f16 v[18:33], v[70:73], v[74:77], v[18:33]
	global_load_lds_dwordx4 v150, s[10:11]
	ds_read_b128 v[110:113], v136 offset:20480
	s_add_u32 m0, s38, 0xd000
	v_mfma_f32_32x32x16_f16 v[2:17], v[70:73], v[78:81], v[2:17]
	global_load_lds_dwordx4 v150, s[8:9]
	ds_read_b128 v[102:105], v132 offset:4096
	s_waitcnt lgkmcnt(6)
	s_add_u32 m0, s38, 0xa000
	v_mfma_f32_32x32x16_f16 v[50:65], v[82:85], v[90:93], v[50:65]
	global_load_lds_dwordx4 v148, s[10:11]
	ds_read_b128 v[114:117], v133 offset:0
	s_waitcnt lgkmcnt(6)
	s_add_u32 m0, s38, 0xe000
	v_mfma_f32_32x32x16_f16 v[34:49], v[82:85], v[94:97], v[34:49]
	global_load_lds_dwordx4 v148, s[8:9]
	ds_read_b128 v[122:125], v137 offset:16384
	s_waitcnt lgkmcnt(6)
	s_add_u32 m0, s38, 0xb000
	v_mfma_f32_32x32x16_f16 v[18:33], v[86:89], v[90:93], v[18:33]
	global_load_lds_dwordx4 v146, s[10:11]
	ds_read_b128 v[126:129], v137 offset:20480
	s_add_u32 m0, s38, 0xf000
	v_mfma_f32_32x32x16_f16 v[2:17], v[86:89], v[94:97], v[2:17]
	global_load_lds_dwordx4 v146, s[8:9]
	ds_read_b128 v[118:121], v133 offset:4096
	s_add_u32 s8, s8, 0x80
	s_addc_u32 s9, s9, 0
	s_add_u32 s10, s10, 0x80
	s_addc_u32 s11, s11, 0
	s_branch .Lwo_dd0

.Lwo_stage1:
	s_cmp_ge_u32 s22, 15
	s_cbranch_scc1 .Lwo_nl1
	s_waitcnt lgkmcnt(6)
	s_add_u32 m0, s38, 0x0
	v_mfma_f32_32x32x16_f16 v[50:65], v[66:69], v[74:77], v[50:65]
	global_load_lds_dwordx4 v152, s[10:11]
	ds_read_b128 v[98:101], v132 offset:32768
	s_waitcnt lgkmcnt(6)
	s_add_u32 m0, s38, 0x4000
	v_mfma_f32_32x32x16_f16 v[34:49], v[66:69], v[78:81], v[34:49]
	global_load_lds_dwordx4 v152, s[8:9]
	ds_read_b128 v[106:109], v136 offset:49152
	s_waitcnt lgkmcnt(6)
	s_add_u32 m0, s38, 0x1000
	v_mfma_f32_32x32x16_f16 v[18:33], v[70:73], v[74:77], v[18:33]
	global_load_lds_dwordx4 v150, s[10:11]
	ds_read_b128 v[110:113], v136 offset:53248
	s_add_u32 m0, s38, 0x5000
	v_mfma_f32_32x32x16_f16 v[2:17], v[70:73], v[78:81], v[2:17]
	global_load_lds_dwordx4 v150, s[8:9]
	ds_read_b128 v[102:105], v132 offset:36864
	s_waitcnt lgkmcnt(6)
	s_add_u32 m0, s38, 0x2000
	v_mfma_f32_32x32x16_f16 v[50:65], v[82:85], v[90:93], v[50:65]
	global_load_lds_dwordx4 v148, s[10:11]
	ds_read_b128 v[114:117], v133 offset:32768
	s_waitcnt lgkmcnt(6)
	s_add_u32 m0, s38, 0x6000
	v_mfma_f32_32x32x16_f16 v[34:49], v[82:85], v[94:97], v[34:49]
	global_load_lds_dwordx4 v148, s[8:9]
	ds_read_b128 v[122:125], v137 offset:49152
	s_waitcnt lgkmcnt(6)
	s_add_u32 m0, s38, 0x3000
	v_mfma_f32_32x32x16_f16 v[18:33], v[86:89], v[90:93], v[18:33]
	global_load_lds_dwordx4 v146, s[10:11]
	ds_read_b128 v[126:129], v137 offset:53248
	s_add_u32 m0, s38, 0x7000
	v_mfma_f32_32x32x16_f16 v[2:17], v[86:89], v[94:97], v[2:17]
	global_load_lds_dwordx4 v146, s[8:9]
	ds_read_b128 v[118:121], v133 offset:36864
	s_add_u32 s8, s8, 0x80
	s_addc_u32 s9, s9, 0
	s_add_u32 s10, s10, 0x80
	s_addc_u32 s11, s11, 0
	s_branch .Lwo_dd1

; DI void gemm_tile_deep(const h16* __restrict__ A, int lda, const h16* __restrict__ B, int ldb, int K, f32x16 (&acc)[2][2], h16* sm) {
;     ...
;   for (int kt = 0; kt < nk; kt += 2) {
;     DEEP_HALF(ra0, rb0, 0, kt)
;     DEEP_HALF(ra1, rb1, 1, kt + 1)
;   }
.Lwo_dd1:
	s_waitcnt lgkmcnt(6)
	v_mfma_f32_32x32x16_f16 v[50:65], v[98:101], v[106:109], v[50:65]
	s_waitcnt lgkmcnt(5)
	v_mfma_f32_32x32x16_f16 v[34:49], v[98:101], v[110:113], v[34:49]
	s_waitcnt lgkmcnt(4)
	v_mfma_f32_32x32x16_f16 v[18:33], v[102:105], v[106:109], v[18:33]
	v_mfma_f32_32x32x16_f16 v[2:17], v[102:105], v[110:113], v[2:17]
	s_waitcnt lgkmcnt(0)
	s_add_i32 s22, s22, 1
	s_cmp_ge_u32 s22, 16
	s_cbranch_scc1 .Lwo_fin
	s_waitcnt vmcnt(0)
	s_barrier
	ds_read_b128 v[66:69], v130 offset:0
	ds_read_b128 v[74:77], v134 offset:16384
	ds_read_b128 v[78:81], v134 offset:20480
	ds_read_b128 v[70:73], v130 offset:4096
	ds_read_b128 v[82:85], v131 offset:0
	ds_read_b128 v[90:93], v135 offset:16384
	ds_read_b128 v[94:97], v135 offset:20480
	ds_read_b128 v[86:89], v131 offset:4096
	v_mfma_f32_32x32x16_f16 v[50:65], v[114:117], v[122:125], v[50:65]
	v_mfma_f32_32x32x16_f16 v[34:49], v[114:117], v[126:129], v[34:49]
	v_mfma_f32_32x32x16_f16 v[18:33], v[118:121], v[122:125], v[18:33]
	v_mfma_f32_32x32x16_f16 v[2:17], v[118:121], v[126:129], v[2:17]
	s_branch .Lwo_stage0

; DI int TIDX() { int t = threadIdx.x; asm volatile("" : "+v"(t)); return t; }
; #define XCD_LOOP_W(Mt, ntn) const int xcd_ = BIDX() & 7; const int Mx_ = ((Mt) + 7) >> 3; for (int u_ = BIDX() >> 3; u_ < Mx_ * (ntn); u_ += (int)(gridDim.x >> 3))
; template <class BR>
; DI void gemm_tile_w(const h16* __restrict__ A, int lda, const h16* __restrict__ B, int ldb, BR brow, int K, f32x16 (&acc)[4][2], h16* sm) {
;   const int tid = TIDX(), lane = tid & 63, w = tid >> 6, wm = w >> 1, wn = w & 1, r = lane & 31, hh = lane >> 5;
;   const unsigned ao = (unsigned)(tid >> 2) * (unsigned)lda + (unsigned)(tid & 3) * 8u;
;   const unsigned bo0 = (unsigned)brow(tid >> 2) * (unsigned)ldb + (unsigned)(tid & 3) * 8u;
;   const unsigned bo1 = (unsigned)brow((tid >> 2) + 64) * (unsigned)ldb + (unsigned)(tid & 3) * 8u;
;   const h16* ag = A;
;   const h16* bg = B;
;   u32x4 ra0[4], rb0[2], ra1[4], rb1[2];
; #pragma unroll
;   for (int i = 0; i < 4; ++i) ra0[i] = *(const u32x4*)(ag + (ao + (unsigned)i * 64u * (unsigned)lda));
;   rb0[0] = *(const u32x4*)(bg + bo0);
;   rb0[1] = *(const u32x4*)(bg + bo1);
;   ag += 32; bg += 32;
; #pragma unroll
;   for (int i = 0; i < 4; ++i) ra1[i] = *(const u32x4*)(ag + (ao + (unsigned)i * 64u * (unsigned)lda));
;   rb1[0] = *(const u32x4*)(bg + bo0);
;   rb1[1] = *(const u32x4*)(bg + bo1);
;   const int nk = K >> 5;
;   const int wofs = (tid >> 2) * LS2 + (tid & 3) * 8;
; DI void phase_proj(const P& p, int l, char* smem) {
;     ...
;   XCD_LOOP_W(136, 27) {
;     int mt_, nt_;
;     tile_map(u_, Mx_, 27, xcd_, mt_, nt_);
;     if (mt_ >= 136) continue;
;     const int m0 = mt_ * 256, n0 = nt_ * 128;
;     f32x16 acc[4][2];
;     zero_acc_w(acc);
;     gemm_tile_w(hbuf + (size_t)m0 * 1024, 1024, W, 1024, [&](int rr) { return n0 + rr; }, 1024, acc, (h16*)smem);
.LBB0_693:
	s_mul_hi_i32 s0, s36, 0x4bda12f7
	s_lshr_b32 s1, s0, 31
	s_ashr_i32 s0, s0, 6
	s_add_i32 s0, s0, s1
	s_lshl_b32 s4, s0, 3
	s_sub_i32 s1, 17, s4
	s_min_u32 s5, s1, 8
	v_cvt_f32_ubyte0_e32 v0, s5
	v_rcp_iflag_f32_e32 v0, v0
	s_sub_i32 s7, 0, s5
	s_mulk_i32 s0, 0xff28
	s_add_i32 s0, s0, s36
	v_mul_f32_e32 v0, 0x4f7ffffe, v0
	v_cvt_u32_f32_e32 v0, v0
	s_abs_i32 s6, s0
	s_ashr_i32 s1, s0, 31
	v_readfirstlane_b32 s8, v0
	s_mul_i32 s7, s7, s8
	s_mul_hi_u32 s7, s8, s7
	s_add_i32 s8, s8, s7
	s_mul_hi_u32 s7, s6, s8
	s_mul_i32 s8, s7, s5
	s_sub_i32 s6, s6, s8
	s_add_i32 s8, s7, 1
	s_sub_i32 s9, s6, s5
	s_cmp_ge_u32 s6, s5
	s_cselect_b32 s7, s8, s7
	s_cselect_b32 s6, s9, s6
	s_add_i32 s8, s7, 1
	s_cmp_ge_u32 s6, s5
	s_cselect_b32 s6, s8, s7
	s_xor_b32 s6, s6, s1
	s_sub_i32 s1, s6, s1
	s_add_i32 s4, s4, s72
	s_mul_i32 s5, s5, s1
	s_add_i32 s4, s4, s0
	s_sub_i32 s0, s4, s5
	s_cmpk_gt_i32 s0, 0x87
	s_cbranch_scc1 .LBB0_692
	s_lshl_b32 s0, s0, 8
	s_lshl_b32 s10, s1, 7
	s_ashr_i32 s1, s0, 31
	v_mov_b32_e32 v14, v203
	s_lshl_b64 s[4:5], s[0:1], 11
	s_add_u32 s4, s69, s4
	v_ashrrev_i32_e32 v15, 2, v14
	v_lshlrev_b32_e32 v0, 3, v14
	v_and_b32_e32 v16, 24, v0
	v_bfe_u32 v17, v14, 4, 2
	v_lshlrev_b32_e32 v17, 3, v17
	v_xor_b32_e32 v16, v16, v17
	v_add_u32_e32 v10, s10, v15
	s_addc_u32 s5, s24, s5
	v_lshl_or_b32 v0, v15, 10, v16
	v_lshl_or_b32 v210, v10, 10, v16
	v_lshl_add_u64 v[2:3], v[0:1], 1, s[4:5]
	v_add_u32_e32 v204, 0x10000, v0
	v_mov_b32_e32 v205, v1
	v_add_u32_e32 v206, 0x20000, v0
	v_mov_b32_e32 v207, v1
	v_add_u32_e32 v208, 0x30000, v0
	v_mov_b32_e32 v209, v1
	v_add_u32_e32 v212, 0x10000, v210
	v_mov_b32_e32 v211, v1
	s_mov_b64 s[6:7], s[54:55]
	v_mov_b32_e32 v213, v1
	v_lshl_add_u64 v[4:5], v[204:205], 1, s[4:5]
	v_lshl_add_u64 v[6:7], v[206:207], 1, s[4:5]
	v_lshl_add_u64 v[8:9], v[208:209], 1, s[4:5]
	v_lshl_add_u64 v[10:11], v[210:211], 1, s[6:7]
	v_lshl_add_u64 v[12:13], v[212:213], 1, s[6:7]
	v_readfirstlane_b32 s18, v203
	s_nop 3
	s_lshr_b32 s18, s18, 6
	s_lshl_b32 s18, s18, 10
	v_and_b32_e32 v136, 31, v203
	v_bfe_u32 v137, v203, 5, 1
	v_bfe_u32 v138, v203, 2, 2
	v_xor_b32_e32 v137, v137, v138
	v_lshlrev_b32_e32 v137, 4, v137
	v_lshl_or_b32 v136, v136, 6, v137
	v_lshrrev_b32_e32 v138, 7, v203
	v_lshl_add_u32 v130, v138, 13, v136
	v_bfe_u32 v138, v203, 6, 1
	v_lshl_add_u32 v132, v138, 12, v136
	v_xor_b32_e32 v131, 32, v130
	v_xor_b32_e32 v133, 32, v132
	v_lshlrev_b32_e32 v139, 1, v0
	v_lshlrev_b32_e32 v140, 1, v204
	v_lshlrev_b32_e32 v141, 1, v206
	v_lshlrev_b32_e32 v142, 1, v208
	v_lshlrev_b32_e32 v143, 1, v210
	v_lshlrev_b32_e32 v144, 1, v212
	s_add_u32 m0, s18, 0x0
	s_nop 0
	global_load_lds_dwordx4 v139, s[4:5]
	s_add_u32 m0, s18, 0x1000
	s_nop 0
	global_load_lds_dwordx4 v140, s[4:5]
	s_add_u32 m0, s18, 0x2000
	s_nop 0
	global_load_lds_dwordx4 v141, s[4:5]
	s_add_u32 m0, s18, 0x3000
	s_nop 0
	global_load_lds_dwordx4 v142, s[4:5]
	s_add_u32 m0, s18, 0x4000
	s_nop 0
	global_load_lds_dwordx4 v143, s[6:7]
	s_add_u32 m0, s18, 0x5000
	s_nop 0
	global_load_lds_dwordx4 v144, s[6:7]
	s_add_u32 s4, s4, 64
	s_addc_u32 s5, s5, 0
	s_add_u32 s6, s6, 64
	s_addc_u32 s7, s7, 0
	v_mov_b32_e32 v114, 0
	s_mov_b32 s1, 0
	v_mov_b32_e32 v115, v114
	v_mov_b32_e32 v116, v114
	s_waitcnt vmcnt(14)
	v_mov_b32_e32 v117, v114
	v_mov_b32_e32 v118, v114
	v_mov_b32_e32 v119, v114
	s_waitcnt vmcnt(13)
	v_mov_b32_e32 v120, v114
	v_mov_b32_e32 v121, v114
	v_mov_b32_e32 v122, v114
	s_waitcnt vmcnt(12)
	v_mov_b32_e32 v123, v114
	v_mov_b32_e32 v124, v114
	v_mov_b32_e32 v125, v114
	v_mov_b32_e32 v126, v114
	v_mov_b32_e32 v127, v114
	v_mov_b32_e32 v128, v114
	v_mov_b32_e32 v129, v114
	v_mov_b32_e32 v98, v114
	v_mov_b32_e32 v99, v114
	v_mov_b32_e32 v100, v114
	v_mov_b32_e32 v101, v114
	v_mov_b32_e32 v102, v114
	v_mov_b32_e32 v103, v114
	v_mov_b32_e32 v104, v114
	v_mov_b32_e32 v105, v114
	v_mov_b32_e32 v106, v114
	v_mov_b32_e32 v107, v114
	v_mov_b32_e32 v108, v114
	v_mov_b32_e32 v109, v114
	v_mov_b32_e32 v110, v114
	v_mov_b32_e32 v111, v114
	v_mov_b32_e32 v112, v114
	v_mov_b32_e32 v113, v114
	v_mov_b32_e32 v82, v114
	v_mov_b32_e32 v83, v114
	v_mov_b32_e32 v84, v114
	v_mov_b32_e32 v85, v114
	v_mov_b32_e32 v86, v114
	v_mov_b32_e32 v87, v114
	v_mov_b32_e32 v88, v114
	v_mov_b32_e32 v89, v114
	v_mov_b32_e32 v90, v114
	v_mov_b32_e32 v91, v114
	v_mov_b32_e32 v92, v114
	v_mov_b32_e32 v93, v114
	v_mov_b32_e32 v94, v114
	v_mov_b32_e32 v95, v114
	v_mov_b32_e32 v96, v114
	v_mov_b32_e32 v97, v114
	v_mov_b32_e32 v66, v114
	v_mov_b32_e32 v67, v114
	v_mov_b32_e32 v68, v114
	v_mov_b32_e32 v69, v114
	v_mov_b32_e32 v70, v114
	v_mov_b32_e32 v71, v114
	v_mov_b32_e32 v72, v114
	v_mov_b32_e32 v73, v114
	v_mov_b32_e32 v74, v114
	v_mov_b32_e32 v75, v114
	v_mov_b32_e32 v76, v114
	v_mov_b32_e32 v77, v114
	v_mov_b32_e32 v78, v114
	v_mov_b32_e32 v79, v114
	v_mov_b32_e32 v80, v114
	v_mov_b32_e32 v81, v114
	v_mov_b32_e32 v50, v114
	v_mov_b32_e32 v51, v114
	v_mov_b32_e32 v52, v114
	v_mov_b32_e32 v53, v114
	v_mov_b32_e32 v54, v114
	v_mov_b32_e32 v55, v114
	v_mov_b32_e32 v56, v114
	v_mov_b32_e32 v57, v114
	v_mov_b32_e32 v58, v114
	v_mov_b32_e32 v59, v114
	v_mov_b32_e32 v60, v114
	v_mov_b32_e32 v61, v114
	v_mov_b32_e32 v62, v114
	v_mov_b32_e32 v63, v114
	v_mov_b32_e32 v64, v114
	v_mov_b32_e32 v65, v114
	v_mov_b32_e32 v34, v114
	v_mov_b32_e32 v35, v114
	v_mov_b32_e32 v36, v114
	v_mov_b32_e32 v37, v114
	v_mov_b32_e32 v38, v114
	v_mov_b32_e32 v39, v114
	v_mov_b32_e32 v40, v114
	v_mov_b32_e32 v41, v114
	v_mov_b32_e32 v42, v114
	v_mov_b32_e32 v43, v114
	v_mov_b32_e32 v44, v114
	v_mov_b32_e32 v45, v114
	v_mov_b32_e32 v46, v114
	v_mov_b32_e32 v47, v114
	v_mov_b32_e32 v48, v114
	v_mov_b32_e32 v49, v114
	v_mov_b32_e32 v18, v114
	v_mov_b32_e32 v19, v114
	v_mov_b32_e32 v20, v114
	v_mov_b32_e32 v21, v114
	v_mov_b32_e32 v22, v114
	v_mov_b32_e32 v23, v114
	v_mov_b32_e32 v24, v114
	v_mov_b32_e32 v25, v114
	v_mov_b32_e32 v26, v114
	v_mov_b32_e32 v27, v114
	v_mov_b32_e32 v28, v114
	v_mov_b32_e32 v29, v114
	v_mov_b32_e32 v30, v114
	v_mov_b32_e32 v31, v114
	v_mov_b32_e32 v32, v114
	v_mov_b32_e32 v33, v114
	v_mov_b32_e32 v2, v114
	v_mov_b32_e32 v3, v114
	v_mov_b32_e32 v4, v114
	v_mov_b32_e32 v5, v114
	v_mov_b32_e32 v6, v114
	v_mov_b32_e32 v7, v114
	v_mov_b32_e32 v8, v114
	v_mov_b32_e32 v9, v114
	v_mov_b32_e32 v10, v114
	v_mov_b32_e32 v11, v114
	v_mov_b32_e32 v12, v114
	v_mov_b32_e32 v13, v114
	v_mov_b32_e32 v14, v114
	v_mov_b32_e32 v15, v114
	v_mov_b32_e32 v16, v114
	v_mov_b32_e32 v17, v114
	s_waitcnt vmcnt(0)
	s_barrier
	ds_read_b128 v[178:181], v130 offset:0
	ds_read_b128 v[194:197], v132 offset:16384
	ds_read_b128 v[198:201], v132 offset:18432
	ds_read_b128 v[182:185], v130 offset:2048
	ds_read_b128 v[186:189], v130 offset:4096
	ds_read_b128 v[190:193], v130 offset:6144
.Lpg_stage0:
	s_cmp_ge_u32 s1, 31
	s_cbranch_scc1 .Lpg_nl0
	s_waitcnt lgkmcnt(4)
	v_mfma_f32_32x32x16_f16 v[114:129], v[178:181], v[194:197], v[114:129]
	ds_read_b128 v[216:219], v131 offset:0
	s_waitcnt lgkmcnt(4)
	s_add_u32 m0, s18, 0x6000
	v_mfma_f32_32x32x16_f16 v[98:113], v[178:181], v[198:201], v[98:113]
	global_load_lds_dwordx4 v139, s[4:5]
	ds_read_b128 v[234:237], v133 offset:16384
	s_waitcnt lgkmcnt(4)
	s_add_u32 m0, s18, 0x7000
	v_mfma_f32_32x32x16_f16 v[82:97], v[182:185], v[194:197], v[82:97]
	global_load_lds_dwordx4 v140, s[4:5]
	ds_read_b128 v[240:243], v133 offset:18432
	s_add_u32 m0, s18, 0x8000
	v_mfma_f32_32x32x16_f16 v[66:81], v[182:185], v[198:201], v[66:81]
	global_load_lds_dwordx4 v141, s[4:5]
	ds_read_b128 v[220:223], v131 offset:2048
	s_waitcnt lgkmcnt(5)
	s_add_u32 m0, s18, 0x9000
	v_mfma_f32_32x32x16_f16 v[50:65], v[186:189], v[194:197], v[50:65]
	global_load_lds_dwordx4 v142, s[4:5]
	ds_read_b128 v[226:229], v131 offset:4096
	s_add_u32 m0, s18, 0xa000
	v_mfma_f32_32x32x16_f16 v[34:49], v[186:189], v[198:201], v[34:49]
	global_load_lds_dwordx4 v143, s[6:7]
	ds_read_b128 v[230:233], v131 offset:6144
	s_waitcnt lgkmcnt(6)
	s_add_u32 m0, s18, 0xb000
	v_mfma_f32_32x32x16_f16 v[18:33], v[190:193], v[194:197], v[18:33]
	global_load_lds_dwordx4 v144, s[6:7]
	v_mfma_f32_32x32x16_f16 v[2:17], v[190:193], v[198:201], v[2:17]
	s_add_u32 s4, s4, 64
	s_addc_u32 s5, s5, 0
	s_add_u32 s6, s6, 64
	s_addc_u32 s7, s7, 0
	s_branch .Lpg_dd0

; template <class BR>
; DI void gemm_tile_w(const h16* __restrict__ A, int lda, const h16* __restrict__ B, int ldb, BR brow, int K, f32x16 (&acc)[4][2], h16* sm) {
;     ...
;   for (int kt = 0; kt < nk; kt += 2) {
;     WIDE_HALF(ra0, rb0, 0, kt)
;     WIDE_HALF(ra1, rb1, 1, kt + 1)
.Lpg_dd0:
	s_waitcnt lgkmcnt(4)
	v_mfma_f32_32x32x16_f16 v[114:129], v[216:219], v[234:237], v[114:129]
	s_waitcnt lgkmcnt(3)
	v_mfma_f32_32x32x16_f16 v[98:113], v[216:219], v[240:243], v[98:113]
	s_waitcnt lgkmcnt(2)
	v_mfma_f32_32x32x16_f16 v[82:97], v[220:223], v[234:237], v[82:97]
	v_mfma_f32_32x32x16_f16 v[66:81], v[220:223], v[240:243], v[66:81]
	s_waitcnt lgkmcnt(0)
	s_add_i32 s1, s1, 1
	s_waitcnt vmcnt(0)
	s_barrier
	ds_read_b128 v[178:181], v130 offset:24576
	ds_read_b128 v[194:197], v132 offset:40960
	ds_read_b128 v[198:201], v132 offset:43008
	ds_read_b128 v[182:185], v130 offset:26624
	ds_read_b128 v[186:189], v130 offset:28672
	ds_read_b128 v[190:193], v130 offset:30720
	v_mfma_f32_32x32x16_f16 v[50:65], v[226:229], v[234:237], v[50:65]
	v_mfma_f32_32x32x16_f16 v[34:49], v[226:229], v[240:243], v[34:49]
	v_mfma_f32_32x32x16_f16 v[18:33], v[230:233], v[234:237], v[18:33]
	v_mfma_f32_32x32x16_f16 v[2:17], v[230:233], v[240:243], v[2:17]
.Lpg_stage1:
	s_cmp_ge_u32 s1, 31
	s_cbranch_scc1 .Lpg_nl1
	s_waitcnt lgkmcnt(4)
	v_mfma_f32_32x32x16_f16 v[114:129], v[178:181], v[194:197], v[114:129]
	ds_read_b128 v[216:219], v131 offset:24576
	s_waitcnt lgkmcnt(4)
	s_add_u32 m0, s18, 0x0
	v_mfma_f32_32x32x16_f16 v[98:113], v[178:181], v[198:201], v[98:113]
	global_load_lds_dwordx4 v139, s[4:5]
	ds_read_b128 v[234:237], v133 offset:40960
	s_waitcnt lgkmcnt(4)
	s_add_u32 m0, s18, 0x1000
	v_mfma_f32_32x32x16_f16 v[82:97], v[182:185], v[194:197], v[82:97]
	global_load_lds_dwordx4 v140, s[4:5]
	ds_read_b128 v[240:243], v133 offset:43008
	s_add_u32 m0, s18, 0x2000
	v_mfma_f32_32x32x16_f16 v[66:81], v[182:185], v[198:201], v[66:81]
	global_load_lds_dwordx4 v141, s[4:5]
	ds_read_b128 v[220:223], v131 offset:26624
	s_waitcnt lgkmcnt(5)
	s_add_u32 m0, s18, 0x3000
	v_mfma_f32_32x32x16_f16 v[50:65], v[186:189], v[194:197], v[50:65]
	global_load_lds_dwordx4 v142, s[4:5]
	ds_read_b128 v[226:229], v131 offset:28672
	s_add_u32 m0, s18, 0x4000
	v_mfma_f32_32x32x16_f16 v[34:49], v[186:189], v[198:201], v[34:49]
	global_load_lds_dwordx4 v143, s[6:7]
	ds_read_b128 v[230:233], v131 offset:30720
	s_waitcnt lgkmcnt(6)
	s_add_u32 m0, s18, 0x5000
	v_mfma_f32_32x32x16_f16 v[18:33], v[190:193], v[194:197], v[18:33]
	global_load_lds_dwordx4 v144, s[6:7]
	v_mfma_f32_32x32x16_f16 v[2:17], v[190:193], v[198:201], v[2:17]
	s_add_u32 s4, s4, 64
	s_addc_u32 s5, s5, 0
	s_add_u32 s6, s6, 64
	s_addc_u32 s7, s7, 0
	s_branch .Lpg_dd1

; template <class BR>
; DI void gemm_tile_w(const h16* __restrict__ A, int lda, const h16* __restrict__ B, int ldb, BR brow, int K, f32x16 (&acc)[4][2], h16* sm) {
;     ...
;   for (int kt = 0; kt < nk; kt += 2) {
;     WIDE_HALF(ra0, rb0, 0, kt)
;     WIDE_HALF(ra1, rb1, 1, kt + 1)
;   }
;     ...
;   __syncthreads();
.Lpg_dd1:
	s_waitcnt lgkmcnt(4)
	v_mfma_f32_32x32x16_f16 v[114:129], v[216:219], v[234:237], v[114:129]
	s_waitcnt lgkmcnt(3)
	v_mfma_f32_32x32x16_f16 v[98:113], v[216:219], v[240:243], v[98:113]
	s_waitcnt lgkmcnt(2)
	v_mfma_f32_32x32x16_f16 v[82:97], v[220:223], v[234:237], v[82:97]
	v_mfma_f32_32x32x16_f16 v[66:81], v[220:223], v[240:243], v[66:81]
	s_waitcnt lgkmcnt(0)
	s_add_i32 s1, s1, 1
	s_cmp_ge_u32 s1, 32
	s_cbranch_scc1 .Lpg_fin
	s_waitcnt vmcnt(0)
	s_barrier
	ds_read_b128 v[178:181], v130 offset:0
	ds_read_b128 v[194:197], v132 offset:16384
	ds_read_b128 v[198:201], v132 offset:18432
	ds_read_b128 v[182:185], v130 offset:2048
	ds_read_b128 v[186:189], v130 offset:4096
	ds_read_b128 v[190:193], v130 offset:6144
	v_mfma_f32_32x32x16_f16 v[50:65], v[226:229], v[234:237], v[50:65]
	v_mfma_f32_32x32x16_f16 v[34:49], v[226:229], v[240:243], v[34:49]
	v_mfma_f32_32x32x16_f16 v[18:33], v[230:233], v[234:237], v[18:33]
	v_mfma_f32_32x32x16_f16 v[2:17], v[230:233], v[240:243], v[2:17]
	s_branch .Lpg_stage0
